# G2 epilogue (X = ALPHA*X + g1*acc): the 64 dependent load->wait->store steps per lane become two batches of 32 loads, one wait each, same mul/fmac per element
# speedup vs baseline: 1.2475x; 1.0359x over previous
.LBB0_639:
	s_waitcnt vmcnt(0)
	v_add_u32_e32 v104, s4, v147
	v_add_u32_e32 v67, 0xfffff000, v104
	v_lshrrev_b32_e32 v67, 10, v67
	v_add_u32_e32 v105, 1, v67
	v_cmp_lt_i32_e32 vcc, s57, v104
	v_readlane_b32 s4, v254, 26
	v_readlane_b32 s5, v254, 27
	v_cndmask_b32_e32 v67, 0, v105, vcc
	v_or_b32_e32 v70, v104, v150
	v_or_b32_e32 v66, s6, v135
	v_add_u32_e32 v107, s40, v67
	v_mov_b64_e32 v[68:69], s[4:5]
	v_mov_b64_e32 v[108:109], s[4:5]
	v_ashrrev_i32_e32 v67, 31, v66
	v_mad_u64_u32 v[108:109], vcc, v107, s63, v[108:109]
	v_lshlrev_b64 v[66:67], 2, v[66:67]
	v_lshl_add_u64 v[108:109], v[108:109], 0, v[66:67]
	global_load_dword v110, v[108:109], off
	global_load_dword v111, v[108:109], off offset:128
	v_or_b32_e32 v106, 32, v104
	v_cmp_lt_i32_e32 vcc, s57, v106
	v_or_b32_e32 v106, v106, v150
	v_cndmask_b32_e32 v107, 0, v105, vcc
	v_add_u32_e32 v107, s40, v107
	v_mad_u64_u32 v[108:109], vcc, v107, s63, v[68:69]
	v_lshl_add_u64 v[108:109], v[108:109], 0, v[66:67]
	global_load_dword v112, v[108:109], off
	global_load_dword v113, v[108:109], off offset:128
	v_mov_b32_e32 v72, v70
	v_ashrrev_i32_e32 v73, 31, v72
	v_lshlrev_b64 v[72:73], 12, v[72:73]
	v_lshl_add_u64 v[72:73], s[92:93], 0, v[72:73]
	v_lshl_add_u64 v[72:73], v[72:73], 0, v[66:67]
	global_load_dword v114, v[72:73], off
	global_load_dword v162, v[72:73], off offset:128
	v_or_b32_e32 v74, 1, v70
	v_ashrrev_i32_e32 v75, 31, v74
	v_lshlrev_b64 v[74:75], 12, v[74:75]
	v_lshl_add_u64 v[74:75], s[92:93], 0, v[74:75]
	v_lshl_add_u64 v[74:75], v[74:75], 0, v[66:67]
	global_load_dword v115, v[74:75], off
	global_load_dword v163, v[74:75], off offset:128
	v_or_b32_e32 v76, 2, v70
	v_ashrrev_i32_e32 v77, 31, v76
	v_lshlrev_b64 v[76:77], 12, v[76:77]
	v_lshl_add_u64 v[76:77], s[92:93], 0, v[76:77]
	v_lshl_add_u64 v[76:77], v[76:77], 0, v[66:67]
	global_load_dword v116, v[76:77], off
	global_load_dword v164, v[76:77], off offset:128
	v_or_b32_e32 v78, 3, v70
	v_ashrrev_i32_e32 v79, 31, v78
	v_lshlrev_b64 v[78:79], 12, v[78:79]
	v_lshl_add_u64 v[78:79], s[92:93], 0, v[78:79]
	v_lshl_add_u64 v[78:79], v[78:79], 0, v[66:67]
	global_load_dword v117, v[78:79], off
	global_load_dword v165, v[78:79], off offset:128
	v_or_b32_e32 v80, 8, v70
	v_ashrrev_i32_e32 v81, 31, v80
	v_lshlrev_b64 v[80:81], 12, v[80:81]
	v_lshl_add_u64 v[80:81], s[92:93], 0, v[80:81]
	v_lshl_add_u64 v[80:81], v[80:81], 0, v[66:67]
	global_load_dword v118, v[80:81], off
	global_load_dword v166, v[80:81], off offset:128
	v_or_b32_e32 v82, 9, v70
	v_ashrrev_i32_e32 v83, 31, v82
	v_lshlrev_b64 v[82:83], 12, v[82:83]
	v_lshl_add_u64 v[82:83], s[92:93], 0, v[82:83]
	v_lshl_add_u64 v[82:83], v[82:83], 0, v[66:67]
	global_load_dword v119, v[82:83], off
	global_load_dword v167, v[82:83], off offset:128
	v_or_b32_e32 v84, 10, v70
	v_ashrrev_i32_e32 v85, 31, v84
	v_lshlrev_b64 v[84:85], 12, v[84:85]
	v_lshl_add_u64 v[84:85], s[92:93], 0, v[84:85]
	v_lshl_add_u64 v[84:85], v[84:85], 0, v[66:67]
	global_load_dword v120, v[84:85], off
	global_load_dword v168, v[84:85], off offset:128
	v_or_b32_e32 v86, 11, v70
	v_ashrrev_i32_e32 v87, 31, v86
	v_lshlrev_b64 v[86:87], 12, v[86:87]
	v_lshl_add_u64 v[86:87], s[92:93], 0, v[86:87]
	v_lshl_add_u64 v[86:87], v[86:87], 0, v[66:67]
	global_load_dword v121, v[86:87], off
	global_load_dword v169, v[86:87], off offset:128
	v_or_b32_e32 v88, 16, v70
	v_ashrrev_i32_e32 v89, 31, v88
	v_lshlrev_b64 v[88:89], 12, v[88:89]
	v_lshl_add_u64 v[88:89], s[92:93], 0, v[88:89]
	v_lshl_add_u64 v[88:89], v[88:89], 0, v[66:67]
	global_load_dword v122, v[88:89], off
	global_load_dword v170, v[88:89], off offset:128
	v_or_b32_e32 v90, 17, v70
	v_ashrrev_i32_e32 v91, 31, v90
	v_lshlrev_b64 v[90:91], 12, v[90:91]
	v_lshl_add_u64 v[90:91], s[92:93], 0, v[90:91]
	v_lshl_add_u64 v[90:91], v[90:91], 0, v[66:67]
	global_load_dword v123, v[90:91], off
	global_load_dword v171, v[90:91], off offset:128
	v_or_b32_e32 v92, 18, v70
	v_ashrrev_i32_e32 v93, 31, v92
	v_lshlrev_b64 v[92:93], 12, v[92:93]
	v_lshl_add_u64 v[92:93], s[92:93], 0, v[92:93]
	v_lshl_add_u64 v[92:93], v[92:93], 0, v[66:67]
	global_load_dword v124, v[92:93], off
	global_load_dword v172, v[92:93], off offset:128
	v_or_b32_e32 v94, 19, v70
	v_ashrrev_i32_e32 v95, 31, v94
	v_lshlrev_b64 v[94:95], 12, v[94:95]
	v_lshl_add_u64 v[94:95], s[92:93], 0, v[94:95]
	v_lshl_add_u64 v[94:95], v[94:95], 0, v[66:67]
	global_load_dword v125, v[94:95], off
	global_load_dword v173, v[94:95], off offset:128
	v_or_b32_e32 v96, 24, v70
	v_ashrrev_i32_e32 v97, 31, v96
	v_lshlrev_b64 v[96:97], 12, v[96:97]
	v_lshl_add_u64 v[96:97], s[92:93], 0, v[96:97]
	v_lshl_add_u64 v[96:97], v[96:97], 0, v[66:67]
	global_load_dword v126, v[96:97], off
	global_load_dword v174, v[96:97], off offset:128
	v_or_b32_e32 v98, 25, v70
	v_ashrrev_i32_e32 v99, 31, v98
	v_lshlrev_b64 v[98:99], 12, v[98:99]
	v_lshl_add_u64 v[98:99], s[92:93], 0, v[98:99]
	v_lshl_add_u64 v[98:99], v[98:99], 0, v[66:67]
	global_load_dword v127, v[98:99], off
	global_load_dword v175, v[98:99], off offset:128
	v_or_b32_e32 v100, 26, v70
	v_ashrrev_i32_e32 v101, 31, v100
	v_lshlrev_b64 v[100:101], 12, v[100:101]
	v_lshl_add_u64 v[100:101], s[92:93], 0, v[100:101]
	v_lshl_add_u64 v[100:101], v[100:101], 0, v[66:67]
	global_load_dword v128, v[100:101], off
	global_load_dword v176, v[100:101], off offset:128
	v_or_b32_e32 v102, 27, v70
	v_ashrrev_i32_e32 v103, 31, v102
	v_lshlrev_b64 v[102:103], 12, v[102:103]
	v_lshl_add_u64 v[102:103], s[92:93], 0, v[102:103]
	v_lshl_add_u64 v[102:103], v[102:103], 0, v[66:67]
	global_load_dword v129, v[102:103], off
	global_load_dword v177, v[102:103], off offset:128
	s_waitcnt vmcnt(0)
	v_mul_f32_e32 v114, 0x3fd744fd, v114
	v_fmac_f32_e32 v114, v50, v110
	v_mul_f32_e32 v162, 0x3fd744fd, v162
	v_fmac_f32_e32 v162, v34, v111
	global_store_dword v[72:73], v114, off
	global_store_dword v[72:73], v162, off offset:128
	v_mul_f32_e32 v115, 0x3fd744fd, v115
	v_fmac_f32_e32 v115, v51, v110
	v_mul_f32_e32 v163, 0x3fd744fd, v163
	v_fmac_f32_e32 v163, v35, v111
	global_store_dword v[74:75], v115, off
	global_store_dword v[74:75], v163, off offset:128
	v_mul_f32_e32 v116, 0x3fd744fd, v116
	v_fmac_f32_e32 v116, v52, v110
	v_mul_f32_e32 v164, 0x3fd744fd, v164
	v_fmac_f32_e32 v164, v36, v111
	global_store_dword v[76:77], v116, off
	global_store_dword v[76:77], v164, off offset:128
	v_mul_f32_e32 v117, 0x3fd744fd, v117
	v_fmac_f32_e32 v117, v53, v110
	v_mul_f32_e32 v165, 0x3fd744fd, v165
	v_fmac_f32_e32 v165, v37, v111
	global_store_dword v[78:79], v117, off
	global_store_dword v[78:79], v165, off offset:128
	v_mul_f32_e32 v118, 0x3fd744fd, v118
	v_fmac_f32_e32 v118, v54, v110
	v_mul_f32_e32 v166, 0x3fd744fd, v166
	v_fmac_f32_e32 v166, v38, v111
	global_store_dword v[80:81], v118, off
	global_store_dword v[80:81], v166, off offset:128
	v_mul_f32_e32 v119, 0x3fd744fd, v119
	v_fmac_f32_e32 v119, v55, v110
	v_mul_f32_e32 v167, 0x3fd744fd, v167
	v_fmac_f32_e32 v167, v39, v111
	global_store_dword v[82:83], v119, off
	global_store_dword v[82:83], v167, off offset:128
	v_mul_f32_e32 v120, 0x3fd744fd, v120
	v_fmac_f32_e32 v120, v56, v110
	v_mul_f32_e32 v168, 0x3fd744fd, v168
	v_fmac_f32_e32 v168, v40, v111
	global_store_dword v[84:85], v120, off
	global_store_dword v[84:85], v168, off offset:128
	v_mul_f32_e32 v121, 0x3fd744fd, v121
	v_fmac_f32_e32 v121, v57, v110
	v_mul_f32_e32 v169, 0x3fd744fd, v169
	v_fmac_f32_e32 v169, v41, v111
	global_store_dword v[86:87], v121, off
	global_store_dword v[86:87], v169, off offset:128
	v_mul_f32_e32 v122, 0x3fd744fd, v122
	v_fmac_f32_e32 v122, v58, v110
	v_mul_f32_e32 v170, 0x3fd744fd, v170
	v_fmac_f32_e32 v170, v42, v111
	global_store_dword v[88:89], v122, off
	global_store_dword v[88:89], v170, off offset:128
	v_mul_f32_e32 v123, 0x3fd744fd, v123
	v_fmac_f32_e32 v123, v59, v110
	v_mul_f32_e32 v171, 0x3fd744fd, v171
	v_fmac_f32_e32 v171, v43, v111
	global_store_dword v[90:91], v123, off
	global_store_dword v[90:91], v171, off offset:128
	v_mul_f32_e32 v124, 0x3fd744fd, v124
	v_fmac_f32_e32 v124, v60, v110
	v_mul_f32_e32 v172, 0x3fd744fd, v172
	v_fmac_f32_e32 v172, v44, v111
	global_store_dword v[92:93], v124, off
	global_store_dword v[92:93], v172, off offset:128
	v_mul_f32_e32 v125, 0x3fd744fd, v125
	v_fmac_f32_e32 v125, v61, v110
	v_mul_f32_e32 v173, 0x3fd744fd, v173
	v_fmac_f32_e32 v173, v45, v111
	global_store_dword v[94:95], v125, off
	global_store_dword v[94:95], v173, off offset:128
	v_mul_f32_e32 v126, 0x3fd744fd, v126
	v_fmac_f32_e32 v126, v62, v110
	v_mul_f32_e32 v174, 0x3fd744fd, v174
	v_fmac_f32_e32 v174, v46, v111
	global_store_dword v[96:97], v126, off
	global_store_dword v[96:97], v174, off offset:128
	v_mul_f32_e32 v127, 0x3fd744fd, v127
	v_fmac_f32_e32 v127, v63, v110
	v_mul_f32_e32 v175, 0x3fd744fd, v175
	v_fmac_f32_e32 v175, v47, v111
	global_store_dword v[98:99], v127, off
	global_store_dword v[98:99], v175, off offset:128
	v_mul_f32_e32 v128, 0x3fd744fd, v128
	v_fmac_f32_e32 v128, v64, v110
	v_mul_f32_e32 v176, 0x3fd744fd, v176
	v_fmac_f32_e32 v176, v48, v111
	global_store_dword v[100:101], v128, off
	global_store_dword v[100:101], v176, off offset:128
	v_mul_f32_e32 v129, 0x3fd744fd, v129
	v_fmac_f32_e32 v129, v65, v110
	v_mul_f32_e32 v177, 0x3fd744fd, v177
	v_fmac_f32_e32 v177, v49, v111
	global_store_dword v[102:103], v129, off
	global_store_dword v[102:103], v177, off offset:128
	v_mov_b32_e32 v72, v106
	v_ashrrev_i32_e32 v73, 31, v72
	v_lshlrev_b64 v[72:73], 12, v[72:73]
	v_lshl_add_u64 v[72:73], s[92:93], 0, v[72:73]
	v_lshl_add_u64 v[72:73], v[72:73], 0, v[66:67]
	global_load_dword v114, v[72:73], off
	global_load_dword v162, v[72:73], off offset:128
	v_or_b32_e32 v74, 1, v106
	v_ashrrev_i32_e32 v75, 31, v74
	v_lshlrev_b64 v[74:75], 12, v[74:75]
	v_lshl_add_u64 v[74:75], s[92:93], 0, v[74:75]
	v_lshl_add_u64 v[74:75], v[74:75], 0, v[66:67]
	global_load_dword v115, v[74:75], off
	global_load_dword v163, v[74:75], off offset:128
	v_or_b32_e32 v76, 2, v106
	v_ashrrev_i32_e32 v77, 31, v76
	v_lshlrev_b64 v[76:77], 12, v[76:77]
	v_lshl_add_u64 v[76:77], s[92:93], 0, v[76:77]
	v_lshl_add_u64 v[76:77], v[76:77], 0, v[66:67]
	global_load_dword v116, v[76:77], off
	global_load_dword v164, v[76:77], off offset:128
	v_or_b32_e32 v78, 3, v106
	v_ashrrev_i32_e32 v79, 31, v78
	v_lshlrev_b64 v[78:79], 12, v[78:79]
	v_lshl_add_u64 v[78:79], s[92:93], 0, v[78:79]
	v_lshl_add_u64 v[78:79], v[78:79], 0, v[66:67]
	global_load_dword v117, v[78:79], off
	global_load_dword v165, v[78:79], off offset:128
	v_or_b32_e32 v80, 8, v106
	v_ashrrev_i32_e32 v81, 31, v80
	v_lshlrev_b64 v[80:81], 12, v[80:81]
	v_lshl_add_u64 v[80:81], s[92:93], 0, v[80:81]
	v_lshl_add_u64 v[80:81], v[80:81], 0, v[66:67]
	global_load_dword v118, v[80:81], off
	global_load_dword v166, v[80:81], off offset:128
	v_or_b32_e32 v82, 9, v106
	v_ashrrev_i32_e32 v83, 31, v82
	v_lshlrev_b64 v[82:83], 12, v[82:83]
	v_lshl_add_u64 v[82:83], s[92:93], 0, v[82:83]
	v_lshl_add_u64 v[82:83], v[82:83], 0, v[66:67]
	global_load_dword v119, v[82:83], off
	global_load_dword v167, v[82:83], off offset:128
	v_or_b32_e32 v84, 10, v106
	v_ashrrev_i32_e32 v85, 31, v84
	v_lshlrev_b64 v[84:85], 12, v[84:85]
	v_lshl_add_u64 v[84:85], s[92:93], 0, v[84:85]
	v_lshl_add_u64 v[84:85], v[84:85], 0, v[66:67]
	global_load_dword v120, v[84:85], off
	global_load_dword v168, v[84:85], off offset:128
	v_or_b32_e32 v86, 11, v106
	v_ashrrev_i32_e32 v87, 31, v86
	v_lshlrev_b64 v[86:87], 12, v[86:87]
	v_lshl_add_u64 v[86:87], s[92:93], 0, v[86:87]
	v_lshl_add_u64 v[86:87], v[86:87], 0, v[66:67]
	global_load_dword v121, v[86:87], off
	global_load_dword v169, v[86:87], off offset:128
	v_or_b32_e32 v88, 16, v106
	v_ashrrev_i32_e32 v89, 31, v88
	v_lshlrev_b64 v[88:89], 12, v[88:89]
	v_lshl_add_u64 v[88:89], s[92:93], 0, v[88:89]
	v_lshl_add_u64 v[88:89], v[88:89], 0, v[66:67]
	global_load_dword v122, v[88:89], off
	global_load_dword v170, v[88:89], off offset:128
	v_or_b32_e32 v90, 17, v106
	v_ashrrev_i32_e32 v91, 31, v90
	v_lshlrev_b64 v[90:91], 12, v[90:91]
	v_lshl_add_u64 v[90:91], s[92:93], 0, v[90:91]
	v_lshl_add_u64 v[90:91], v[90:91], 0, v[66:67]
	global_load_dword v123, v[90:91], off
	global_load_dword v171, v[90:91], off offset:128
	v_or_b32_e32 v92, 18, v106
	v_ashrrev_i32_e32 v93, 31, v92
	v_lshlrev_b64 v[92:93], 12, v[92:93]
	v_lshl_add_u64 v[92:93], s[92:93], 0, v[92:93]
	v_lshl_add_u64 v[92:93], v[92:93], 0, v[66:67]
	global_load_dword v124, v[92:93], off
	global_load_dword v172, v[92:93], off offset:128
	v_or_b32_e32 v94, 19, v106
	v_ashrrev_i32_e32 v95, 31, v94
	v_lshlrev_b64 v[94:95], 12, v[94:95]
	v_lshl_add_u64 v[94:95], s[92:93], 0, v[94:95]
	v_lshl_add_u64 v[94:95], v[94:95], 0, v[66:67]
	global_load_dword v125, v[94:95], off
	global_load_dword v173, v[94:95], off offset:128
	v_or_b32_e32 v96, 24, v106
	v_ashrrev_i32_e32 v97, 31, v96
	v_lshlrev_b64 v[96:97], 12, v[96:97]
	v_lshl_add_u64 v[96:97], s[92:93], 0, v[96:97]
	v_lshl_add_u64 v[96:97], v[96:97], 0, v[66:67]
	global_load_dword v126, v[96:97], off
	global_load_dword v174, v[96:97], off offset:128
	v_or_b32_e32 v98, 25, v106
	v_ashrrev_i32_e32 v99, 31, v98
	v_lshlrev_b64 v[98:99], 12, v[98:99]
	v_lshl_add_u64 v[98:99], s[92:93], 0, v[98:99]
	v_lshl_add_u64 v[98:99], v[98:99], 0, v[66:67]
	global_load_dword v127, v[98:99], off
	global_load_dword v175, v[98:99], off offset:128
	v_or_b32_e32 v100, 26, v106
	v_ashrrev_i32_e32 v101, 31, v100
	v_lshlrev_b64 v[100:101], 12, v[100:101]
	v_lshl_add_u64 v[100:101], s[92:93], 0, v[100:101]
	v_lshl_add_u64 v[100:101], v[100:101], 0, v[66:67]
	global_load_dword v128, v[100:101], off
	global_load_dword v176, v[100:101], off offset:128
	v_or_b32_e32 v102, 27, v106
	v_ashrrev_i32_e32 v103, 31, v102
	v_lshlrev_b64 v[102:103], 12, v[102:103]
	v_lshl_add_u64 v[102:103], s[92:93], 0, v[102:103]
	v_lshl_add_u64 v[102:103], v[102:103], 0, v[66:67]
	global_load_dword v129, v[102:103], off
	global_load_dword v177, v[102:103], off offset:128
	s_waitcnt vmcnt(0)
	v_mul_f32_e32 v114, 0x3fd744fd, v114
	v_fmac_f32_e32 v114, v18, v112
	v_mul_f32_e32 v162, 0x3fd744fd, v162
	v_fmac_f32_e32 v162, v2, v113
	global_store_dword v[72:73], v114, off
	global_store_dword v[72:73], v162, off offset:128
	v_mul_f32_e32 v115, 0x3fd744fd, v115
	v_fmac_f32_e32 v115, v19, v112
	v_mul_f32_e32 v163, 0x3fd744fd, v163
	v_fmac_f32_e32 v163, v3, v113
	global_store_dword v[74:75], v115, off
	global_store_dword v[74:75], v163, off offset:128
	v_mul_f32_e32 v116, 0x3fd744fd, v116
	v_fmac_f32_e32 v116, v20, v112
	v_mul_f32_e32 v164, 0x3fd744fd, v164
	v_fmac_f32_e32 v164, v4, v113
	global_store_dword v[76:77], v116, off
	global_store_dword v[76:77], v164, off offset:128
	v_mul_f32_e32 v117, 0x3fd744fd, v117
	v_fmac_f32_e32 v117, v21, v112
	v_mul_f32_e32 v165, 0x3fd744fd, v165
	v_fmac_f32_e32 v165, v5, v113
	global_store_dword v[78:79], v117, off
	global_store_dword v[78:79], v165, off offset:128
	v_mul_f32_e32 v118, 0x3fd744fd, v118
	v_fmac_f32_e32 v118, v22, v112
	v_mul_f32_e32 v166, 0x3fd744fd, v166
	v_fmac_f32_e32 v166, v6, v113
	global_store_dword v[80:81], v118, off
	global_store_dword v[80:81], v166, off offset:128
	v_mul_f32_e32 v119, 0x3fd744fd, v119
	v_fmac_f32_e32 v119, v23, v112
	v_mul_f32_e32 v167, 0x3fd744fd, v167
	v_fmac_f32_e32 v167, v7, v113
	global_store_dword v[82:83], v119, off
	global_store_dword v[82:83], v167, off offset:128
	v_mul_f32_e32 v120, 0x3fd744fd, v120
	v_fmac_f32_e32 v120, v24, v112
	v_mul_f32_e32 v168, 0x3fd744fd, v168
	v_fmac_f32_e32 v168, v8, v113
	global_store_dword v[84:85], v120, off
	global_store_dword v[84:85], v168, off offset:128
	v_mul_f32_e32 v121, 0x3fd744fd, v121
	v_fmac_f32_e32 v121, v25, v112
	v_mul_f32_e32 v169, 0x3fd744fd, v169
	v_fmac_f32_e32 v169, v9, v113
	global_store_dword v[86:87], v121, off
	global_store_dword v[86:87], v169, off offset:128
	v_mul_f32_e32 v122, 0x3fd744fd, v122
	v_fmac_f32_e32 v122, v26, v112
	v_mul_f32_e32 v170, 0x3fd744fd, v170
	v_fmac_f32_e32 v170, v10, v113
	global_store_dword v[88:89], v122, off
	global_store_dword v[88:89], v170, off offset:128
	v_mul_f32_e32 v123, 0x3fd744fd, v123
	v_fmac_f32_e32 v123, v27, v112
	v_mul_f32_e32 v171, 0x3fd744fd, v171
	v_fmac_f32_e32 v171, v11, v113
	global_store_dword v[90:91], v123, off
	global_store_dword v[90:91], v171, off offset:128
	v_mul_f32_e32 v124, 0x3fd744fd, v124
	v_fmac_f32_e32 v124, v28, v112
	v_mul_f32_e32 v172, 0x3fd744fd, v172
	v_fmac_f32_e32 v172, v12, v113
	global_store_dword v[92:93], v124, off
	global_store_dword v[92:93], v172, off offset:128
	v_mul_f32_e32 v125, 0x3fd744fd, v125
	v_fmac_f32_e32 v125, v29, v112
	v_mul_f32_e32 v173, 0x3fd744fd, v173
	v_fmac_f32_e32 v173, v13, v113
	global_store_dword v[94:95], v125, off
	global_store_dword v[94:95], v173, off offset:128
	v_mul_f32_e32 v126, 0x3fd744fd, v126
	v_fmac_f32_e32 v126, v30, v112
	v_mul_f32_e32 v174, 0x3fd744fd, v174
	v_fmac_f32_e32 v174, v14, v113
	global_store_dword v[96:97], v126, off
	global_store_dword v[96:97], v174, off offset:128
	v_mul_f32_e32 v127, 0x3fd744fd, v127
	v_fmac_f32_e32 v127, v31, v112
	v_mul_f32_e32 v175, 0x3fd744fd, v175
	v_fmac_f32_e32 v175, v15, v113
	global_store_dword v[98:99], v127, off
	global_store_dword v[98:99], v175, off offset:128
	v_mul_f32_e32 v128, 0x3fd744fd, v128
	v_fmac_f32_e32 v128, v32, v112
	v_mul_f32_e32 v176, 0x3fd744fd, v176
	v_fmac_f32_e32 v176, v16, v113
	global_store_dword v[100:101], v128, off
	global_store_dword v[100:101], v176, off offset:128
	v_mul_f32_e32 v129, 0x3fd744fd, v129
	v_fmac_f32_e32 v129, v33, v112
	v_mul_f32_e32 v177, 0x3fd744fd, v177
	v_fmac_f32_e32 v177, v17, v113
	global_store_dword v[102:103], v129, off
	global_store_dword v[102:103], v177, off offset:128
	s_cmp_gt_u32 s33, 47
	s_cbranch_scc1 .LBB0_642
	s_barrier
	s_and_saveexec_b64 s[4:5], s[14:15]
	s_xor_b64 s[4:5], exec, s[4:5]
	s_cbranch_execz .LBB0_628
	s_mov_b64 s[8:9], exec
	v_mbcnt_lo_u32_b32 v2, s8, 0
	v_mbcnt_hi_u32_b32 v2, s9, v2
	v_cmp_eq_u32_e32 vcc, 0, v2
	s_and_saveexec_b64 s[6:7], vcc
	s_cbranch_execz .LBB0_627
	s_bcnt1_i32_b64 s8, s[8:9]
	v_mov_b32_e32 v3, s8
	global_atomic_add v3, v1, v3, s[2:3] sc0
	s_branch .LBB0_627
